# helper wave starts the XCD L2 writeback as soon as its workgroup reaches a global barrier (overlaps writeback with arrival skew)
# baseline (speedup 1.0000x reference)
; __device__ __forceinline__ unsigned xb_add(unsigned* p, unsigned v) { return __hip_atomic_fetch_add(p, v, __ATOMIC_RELAXED, __HIP_MEMORY_SCOPE_AGENT); }
; __device__ __forceinline__ void xcd_barrier(const XcdBarrier& b) {
;     asm volatile("s_waitcnt vmcnt(0)" ::: "memory");
;     __syncthreads();
;     if (threadIdx.x == 0) {
;         unsigned* bar = b.bar;
;         __builtin_amdgcn_s_waitcnt(0);
;         unsigned nloc = b.st[0], nx = b.st[1];
;         if (nloc == 0u) { xcd_barrier_complete(bar, b.x, nloc, nx); b.st[0] = nloc; b.st[1] = nx; }
;         const unsigned old = xb_add(&bar[XB_XSUB(b.x)], 1u);
;         const unsigned gen = old / nloc;
;         if (old + 1u == (gen + 1u) * nloc) {
;             __builtin_amdgcn_fence(__ATOMIC_RELEASE, "agent");
.LBB0_334:
	s_load_dwordx2 s[6:7], s[58:59], 0xb8
	s_waitcnt lgkmcnt(0)
	s_getreg_b32 s2, hwreg(HW_REG_XCC_ID, 0, 4)
	s_waitcnt vmcnt(0)
	s_barrier
	v_readfirstlane_b32 s100, v228
	s_cmp_eq_u32 s100, 64
	s_cbranch_scc0 .Lskip_wb6
	v_readlane_b32 s100, v255, 4
	s_cmp_eq_u32 s100, 0
	s_cbranch_scc0 .Lskip_wb6
	buffer_wbl2 sc1
	s_waitcnt vmcnt(0)
.Lskip_wb6:
	s_and_saveexec_b64 s[4:5], s[62:63]
	s_xor_b64 s[4:5], exec, s[4:5]
	s_cbranch_execz .LBB0_387
	v_mov_b32_e32 v0, 0x21000
	ds_read_b32 v1, v0
	ds_read_b32 v2, v0 offset:8
	s_waitcnt lgkmcnt(0)
	v_readfirstlane_b32 s10, v1
	v_readfirstlane_b32 s11, v2
	s_cmp_eq_u32 s10, 0
	s_cbranch_scc1 .Lxbo_2
	v_readlane_b32 s12, v255, 4
	s_cmp_eq_u32 s12, 2
	s_cbranch_scc0 .Lxbo_2
	s_cmp_lg_u32 s11, 0
	s_cbranch_scc1 .Lxbf_2
	v_mov_b32_e32 v16, 0x9783580
	global_load_dwordx4 v[0:3], v16, s[6:7] sc1
	global_load_dwordx4 v[4:7], v16, s[6:7] offset:16 sc1
	global_load_dwordx4 v[8:11], v16, s[6:7] offset:32 sc1
	global_load_dwordx4 v[12:15], v16, s[6:7] offset:48 sc1
	s_waitcnt vmcnt(0)
	v_add_u32_e32 v0, v0, v8
	v_add_u32_e32 v1, v1, v9
	v_add_u32_e32 v2, v2, v10
	v_add_u32_e32 v3, v3, v11
	v_add_u32_e32 v4, v4, v12
	v_add_u32_e32 v5, v5, v13
	v_add_u32_e32 v6, v6, v14
	v_add_u32_e32 v7, v7, v15
	v_xor_b32_e32 v0, 15, v0
	v_xor_b32_e32 v1, 15, v1
	v_xor_b32_e32 v2, 15, v2
	v_xor_b32_e32 v3, 15, v3
	v_xor_b32_e32 v4, 15, v4
	v_xor_b32_e32 v5, 15, v5
	v_xor_b32_e32 v6, 15, v6
	v_xor_b32_e32 v7, 15, v7
	v_or3_b32 v1, v1, v2, v3
	v_or3_b32 v4, v4, v5, v6
	v_or3_b32 v1, v1, v4, v7
	v_or_b32_e32 v1, v1, v0
	s_nop 0
	v_readfirstlane_b32 s11, v1
	s_cmp_eq_u32 s11, 0
	s_cselect_b32 s11, 1, 2
	v_mov_b32_e32 v2, s11
	v_mov_b32_e32 v0, 0x21000
	ds_write_b32 v0, v2 offset:8
	s_waitcnt lgkmcnt(0)

; __device__ __forceinline__ unsigned xb_ld(unsigned* p)              { return __hip_atomic_load(p, __ATOMIC_RELAXED, __HIP_MEMORY_SCOPE_AGENT); }
; __device__ __forceinline__ unsigned xb_add(unsigned* p, unsigned v) { return __hip_atomic_fetch_add(p, v, __ATOMIC_RELAXED, __HIP_MEMORY_SCOPE_AGENT); }
; __device__ __forceinline__ void xcd_barrier_complete(unsigned* bar, unsigned x, unsigned& nloc, unsigned& nx) {
;     const unsigned G = gridDim.x * gridDim.y * gridDim.z;
;     unsigned sum, cnt, mine, sp = 0u;
;     for (;;) {
;         sum = 0u; cnt = 0u; mine = 0u;
; #pragma unroll
;         for (unsigned j = 0; j < 16; ++j) { const unsigned c = xb_ld(&bar[XB_XCNT(j)]); sum += c; cnt += (c > 0u) ? 1u : 0u; mine = (j == x) ? c : mine; }
; __device__ __forceinline__ void xcd_barrier(const XcdBarrier& b) {
;     asm volatile("s_waitcnt vmcnt(0)" ::: "memory");
;     __syncthreads();
;     if (threadIdx.x == 0) {
;         unsigned* bar = b.bar;
;         __builtin_amdgcn_s_waitcnt(0);
;         unsigned nloc = b.st[0], nx = b.st[1];
;         if (nloc == 0u) { xcd_barrier_complete(bar, b.x, nloc, nx); b.st[0] = nloc; b.st[1] = nx; }
;         const unsigned old = xb_add(&bar[XB_XSUB(b.x)], 1u);
;         const unsigned gen = old / nloc;
.LBB0_464:
	s_load_dwordx2 s[6:7], s[58:59], 0xb8
	s_waitcnt lgkmcnt(0)
	s_getreg_b32 s2, hwreg(HW_REG_XCC_ID, 0, 4)
	s_waitcnt vmcnt(0)
	s_waitcnt lgkmcnt(0)
	s_barrier
	v_readfirstlane_b32 s100, v228
	s_cmp_eq_u32 s100, 64
	s_cbranch_scc0 .Lskip_wb5
	buffer_wbl2 sc1
	s_waitcnt vmcnt(0)
.Lskip_wb5:
	s_and_saveexec_b64 s[4:5], s[62:63]
	s_xor_b64 s[4:5], exec, s[4:5]
	s_cbranch_execz .LBB0_517
	v_readlane_b32 s10, v254, 31
	s_waitcnt vmcnt(0) expcnt(0) lgkmcnt(0)
	s_and_b32 s2, s2, 15
	v_mov_b32_e32 v0, s10
	ds_read_b32 v2, v0
	v_readlane_b32 s10, v254, 32
	s_waitcnt lgkmcnt(0)
	v_cmp_ne_u32_e32 vcc, 0, v2
	v_mov_b32_e32 v0, s10
	ds_read_b32 v0, v0
	s_cbranch_vccnz .LBB0_480
	s_add_u32 s10, s6, 0x9780200
	s_addc_u32 s11, s7, 0
	s_add_u32 s12, s6, 0x9780400
	s_addc_u32 s13, s7, 0
	s_add_u32 s14, s6, 0x9780500
	s_addc_u32 s15, s7, 0
	s_add_u32 s16, s6, 0x9780600
	s_addc_u32 s17, s7, 0
	s_add_u32 s18, s6, 0x9780700
	s_addc_u32 s19, s7, 0
	s_add_u32 s20, s6, 0x9780800
	s_addc_u32 s21, s7, 0
	s_add_u32 s22, s6, 0x9780900
	s_addc_u32 s23, s7, 0
	s_add_u32 s24, s6, 0x9780a00
	s_addc_u32 s25, s7, 0
	s_add_u32 s26, s6, 0x9780b00
	s_addc_u32 s27, s7, 0
	s_add_u32 s28, s6, 0x9780c00
	s_addc_u32 s29, s7, 0
	s_add_u32 s30, s6, 0x9780d00
	s_addc_u32 s31, s7, 0
	s_add_u32 s34, s6, 0x9780e00
	s_addc_u32 s35, s7, 0
	s_add_u32 s36, s6, 0x9780f00
	s_addc_u32 s37, s7, 0
	s_add_u32 s38, s6, 0x9781000
	s_addc_u32 s39, s7, 0
	s_add_u32 s40, s6, 0x9781100
	s_addc_u32 s41, s7, 0
	s_add_u32 s42, s6, 0x9781200
	s_addc_u32 s43, s7, 0
	s_add_u32 s44, s6, 0x9781300
	s_addc_u32 s45, s7, 0
	s_mov_b32 s52, 1
	s_branch .LBB0_468

; __device__ __forceinline__ unsigned xb_ld(unsigned* p)              { return __hip_atomic_load(p, __ATOMIC_RELAXED, __HIP_MEMORY_SCOPE_AGENT); }
; __device__ __forceinline__ unsigned xb_add(unsigned* p, unsigned v) { return __hip_atomic_fetch_add(p, v, __ATOMIC_RELAXED, __HIP_MEMORY_SCOPE_AGENT); }
; __device__ __forceinline__ void xcd_barrier_complete(unsigned* bar, unsigned x, unsigned& nloc, unsigned& nx) {
;     const unsigned G = gridDim.x * gridDim.y * gridDim.z;
;     unsigned sum, cnt, mine, sp = 0u;
;     for (;;) {
;         sum = 0u; cnt = 0u; mine = 0u;
; #pragma unroll
;         for (unsigned j = 0; j < 16; ++j) { const unsigned c = xb_ld(&bar[XB_XCNT(j)]); sum += c; cnt += (c > 0u) ? 1u : 0u; mine = (j == x) ? c : mine; }
; __device__ __forceinline__ void xcd_barrier(const XcdBarrier& b) {
;     asm volatile("s_waitcnt vmcnt(0)" ::: "memory");
;     __syncthreads();
;     if (threadIdx.x == 0) {
;         unsigned* bar = b.bar;
;         __builtin_amdgcn_s_waitcnt(0);
;         unsigned nloc = b.st[0], nx = b.st[1];
;         if (nloc == 0u) { xcd_barrier_complete(bar, b.x, nloc, nx); b.st[0] = nloc; b.st[1] = nx; }
;         const unsigned old = xb_add(&bar[XB_XSUB(b.x)], 1u);
;         const unsigned gen = old / nloc;
.LBB0_587:
	s_load_dwordx2 s[6:7], s[58:59], 0xb8
	s_waitcnt lgkmcnt(0)
	s_getreg_b32 s2, hwreg(HW_REG_XCC_ID, 0, 4)
	s_waitcnt vmcnt(0)
	s_barrier
	v_readfirstlane_b32 s100, v228
	s_cmp_eq_u32 s100, 64
	s_cbranch_scc0 .Lskip_wb4
	buffer_wbl2 sc1
	s_waitcnt vmcnt(0)
.Lskip_wb4:
	s_and_saveexec_b64 s[4:5], s[62:63]
	s_xor_b64 s[4:5], exec, s[4:5]
	s_cbranch_execz .LBB0_640
	v_readlane_b32 s8, v254, 31
	s_waitcnt vmcnt(0) expcnt(0) lgkmcnt(0)
	s_and_b32 s2, s2, 15
	v_mov_b32_e32 v0, s8
	ds_read_b32 v2, v0
	v_readlane_b32 s8, v254, 32
	s_waitcnt lgkmcnt(0)
	v_cmp_ne_u32_e32 vcc, 0, v2
	v_mov_b32_e32 v0, s8
	ds_read_b32 v0, v0
	s_cbranch_vccnz .LBB0_603
	s_add_u32 s8, s6, 0x9780200
	s_addc_u32 s9, s7, 0
	s_add_u32 s10, s6, 0x9780400
	s_addc_u32 s11, s7, 0
	s_add_u32 s12, s6, 0x9780500
	s_addc_u32 s13, s7, 0
	s_add_u32 s14, s6, 0x9780600
	s_addc_u32 s15, s7, 0
	s_add_u32 s16, s6, 0x9780700
	s_addc_u32 s17, s7, 0
	s_add_u32 s18, s6, 0x9780800
	s_addc_u32 s19, s7, 0
	s_add_u32 s20, s6, 0x9780900
	s_addc_u32 s21, s7, 0
	s_add_u32 s22, s6, 0x9780a00
	s_addc_u32 s23, s7, 0
	s_add_u32 s24, s6, 0x9780b00
	s_addc_u32 s25, s7, 0
	s_add_u32 s26, s6, 0x9780c00
	s_addc_u32 s27, s7, 0
	s_add_u32 s28, s6, 0x9780d00
	s_addc_u32 s29, s7, 0
	s_add_u32 s30, s6, 0x9780e00
	s_addc_u32 s31, s7, 0
	s_add_u32 s34, s6, 0x9780f00
	s_addc_u32 s35, s7, 0
	s_add_u32 s36, s6, 0x9781000
	s_addc_u32 s37, s7, 0
	s_add_u32 s38, s6, 0x9781100
	s_addc_u32 s39, s7, 0
	s_add_u32 s40, s6, 0x9781200
	s_addc_u32 s41, s7, 0
	s_add_u32 s42, s6, 0x9781300
	s_addc_u32 s43, s7, 0
	s_mov_b32 s50, 1
	s_branch .LBB0_591

; __device__ __forceinline__ unsigned xb_ld(unsigned* p)              { return __hip_atomic_load(p, __ATOMIC_RELAXED, __HIP_MEMORY_SCOPE_AGENT); }
; __device__ __forceinline__ unsigned xb_add(unsigned* p, unsigned v) { return __hip_atomic_fetch_add(p, v, __ATOMIC_RELAXED, __HIP_MEMORY_SCOPE_AGENT); }
; __device__ __forceinline__ void xcd_barrier_complete(unsigned* bar, unsigned x, unsigned& nloc, unsigned& nx) {
;     const unsigned G = gridDim.x * gridDim.y * gridDim.z;
;     unsigned sum, cnt, mine, sp = 0u;
;     for (;;) {
;         sum = 0u; cnt = 0u; mine = 0u;
; #pragma unroll
;         for (unsigned j = 0; j < 16; ++j) { const unsigned c = xb_ld(&bar[XB_XCNT(j)]); sum += c; cnt += (c > 0u) ? 1u : 0u; mine = (j == x) ? c : mine; }
; __device__ __forceinline__ void xcd_barrier(const XcdBarrier& b) {
;     asm volatile("s_waitcnt vmcnt(0)" ::: "memory");
;     __syncthreads();
;     if (threadIdx.x == 0) {
;         unsigned* bar = b.bar;
;         __builtin_amdgcn_s_waitcnt(0);
;         unsigned nloc = b.st[0], nx = b.st[1];
;         if (nloc == 0u) { xcd_barrier_complete(bar, b.x, nloc, nx); b.st[0] = nloc; b.st[1] = nx; }
;         const unsigned old = xb_add(&bar[XB_XSUB(b.x)], 1u);
;         const unsigned gen = old / nloc;
.Lskip_wb2:
	s_and_saveexec_b64 s[4:5], s[62:63]
	s_xor_b64 s[4:5], exec, s[4:5]
	s_cbranch_execz .LBB0_979
	v_readlane_b32 s8, v254, 31
	s_waitcnt vmcnt(0) expcnt(0) lgkmcnt(0)
	s_and_b32 s2, s2, 15
	v_mov_b32_e32 v0, s8
	ds_read_b32 v2, v0
	v_readlane_b32 s8, v254, 32
	s_waitcnt lgkmcnt(0)
	v_cmp_ne_u32_e32 vcc, 0, v2
	v_mov_b32_e32 v0, s8
	ds_read_b32 v0, v0
	s_cbranch_vccnz .LBB0_942
	s_add_u32 s8, s6, 0x9780200
	s_addc_u32 s9, s7, 0
	s_add_u32 s10, s6, 0x9780400
	s_addc_u32 s11, s7, 0
	s_add_u32 s12, s6, 0x9780500
	s_addc_u32 s13, s7, 0
	s_add_u32 s14, s6, 0x9780600
	s_addc_u32 s15, s7, 0
	s_add_u32 s18, s6, 0x9780700
	s_addc_u32 s19, s7, 0
	s_add_u32 s20, s6, 0x9780800
	s_addc_u32 s21, s7, 0
	s_add_u32 s22, s6, 0x9780900
	s_addc_u32 s23, s7, 0
	s_add_u32 s24, s6, 0x9780a00
	s_addc_u32 s25, s7, 0
	s_add_u32 s26, s6, 0x9780b00
	s_addc_u32 s27, s7, 0
	s_add_u32 s28, s6, 0x9780c00
	s_addc_u32 s29, s7, 0
	s_add_u32 s30, s6, 0x9780d00
	s_addc_u32 s31, s7, 0
	s_add_u32 s34, s6, 0x9780e00
	s_addc_u32 s35, s7, 0
	s_add_u32 s36, s6, 0x9780f00
	s_addc_u32 s37, s7, 0
	s_add_u32 s38, s6, 0x9781000
	s_addc_u32 s39, s7, 0
	s_add_u32 s40, s6, 0x9781100
	s_addc_u32 s41, s7, 0
	s_add_u32 s42, s6, 0x9781200
	s_addc_u32 s43, s7, 0
	s_add_u32 s44, s6, 0x9781300
	s_addc_u32 s45, s7, 0
	s_mov_b32 s52, 1
	s_branch .LBB0_930

; __device__ __forceinline__ unsigned xb_ld(unsigned* p)              { return __hip_atomic_load(p, __ATOMIC_RELAXED, __HIP_MEMORY_SCOPE_AGENT); }
; __device__ __forceinline__ unsigned xb_add(unsigned* p, unsigned v) { return __hip_atomic_fetch_add(p, v, __ATOMIC_RELAXED, __HIP_MEMORY_SCOPE_AGENT); }
; __device__ __forceinline__ void xcd_barrier_complete(unsigned* bar, unsigned x, unsigned& nloc, unsigned& nx) {
;     const unsigned G = gridDim.x * gridDim.y * gridDim.z;
;     unsigned sum, cnt, mine, sp = 0u;
;     for (;;) {
;         sum = 0u; cnt = 0u; mine = 0u;
; #pragma unroll
;         for (unsigned j = 0; j < 16; ++j) { const unsigned c = xb_ld(&bar[XB_XCNT(j)]); sum += c; cnt += (c > 0u) ? 1u : 0u; mine = (j == x) ? c : mine; }
; __device__ __forceinline__ void xcd_barrier(const XcdBarrier& b) {
;     asm volatile("s_waitcnt vmcnt(0)" ::: "memory");
;     __syncthreads();
;     if (threadIdx.x == 0) {
;         unsigned* bar = b.bar;
;         __builtin_amdgcn_s_waitcnt(0);
;         unsigned nloc = b.st[0], nx = b.st[1];
;         if (nloc == 0u) { xcd_barrier_complete(bar, b.x, nloc, nx); b.st[0] = nloc; b.st[1] = nx; }
;         const unsigned old = xb_add(&bar[XB_XSUB(b.x)], 1u);
;         const unsigned gen = old / nloc;
.LBB0_982:
	s_movk_i32 s60, 0xc0
	s_or_b64 exec, exec, s[4:5]
	s_load_dwordx2 s[4:5], s[58:59], 0xb8
	s_waitcnt lgkmcnt(0)
	s_getreg_b32 s2, hwreg(HW_REG_XCC_ID, 0, 4)
	s_waitcnt vmcnt(0)
	s_barrier
	v_readfirstlane_b32 s100, v228
	s_cmp_eq_u32 s100, 64
	s_cbranch_scc0 .Lskip_wb1
	buffer_wbl2 sc1
	s_waitcnt vmcnt(0)
.Lskip_wb1:
	s_and_saveexec_b64 s[0:1], s[62:63]
	s_xor_b64 s[0:1], exec, s[0:1]
	s_cbranch_execz .LBB0_1035
	v_readlane_b32 s6, v254, 31
	s_waitcnt vmcnt(0) expcnt(0) lgkmcnt(0)
	s_and_b32 s2, s2, 15
	v_mov_b32_e32 v0, s6
	ds_read_b32 v2, v0
	v_readlane_b32 s6, v254, 32
	s_waitcnt lgkmcnt(0)
	v_cmp_ne_u32_e32 vcc, 0, v2
	v_mov_b32_e32 v0, s6
	ds_read_b32 v0, v0
	s_cbranch_vccnz .LBB0_998
	s_add_u32 s6, s4, 0x9780200
	s_addc_u32 s7, s5, 0
	s_add_u32 s12, s4, 0x9780400
	s_addc_u32 s13, s5, 0
	s_add_u32 s14, s4, 0x9780500
	s_addc_u32 s15, s5, 0
	s_add_u32 s18, s4, 0x9780600
	s_addc_u32 s19, s5, 0
	s_add_u32 s20, s4, 0x9780700
	s_addc_u32 s21, s5, 0
	s_add_u32 s22, s4, 0x9780800
	s_addc_u32 s23, s5, 0
	s_add_u32 s24, s4, 0x9780900
	s_addc_u32 s25, s5, 0
	s_add_u32 s26, s4, 0x9780a00
	s_addc_u32 s27, s5, 0
	s_add_u32 s28, s4, 0x9780b00
	s_addc_u32 s29, s5, 0
	s_add_u32 s30, s4, 0x9780c00
	s_addc_u32 s31, s5, 0
	s_add_u32 s34, s4, 0x9780d00
	s_addc_u32 s35, s5, 0
	s_add_u32 s36, s4, 0x9780e00
	s_addc_u32 s37, s5, 0
	s_add_u32 s38, s4, 0x9780f00
	s_addc_u32 s39, s5, 0
	s_add_u32 s40, s4, 0x9781000
	s_addc_u32 s41, s5, 0
	s_add_u32 s42, s4, 0x9781100
	s_addc_u32 s43, s5, 0
	s_add_u32 s44, s4, 0x9781200
	s_addc_u32 s45, s5, 0
	s_add_u32 s46, s4, 0x9781300
	s_mov_b32 s78, s56
	s_addc_u32 s47, s5, 0
	s_mov_b32 s56, 1
	s_branch .LBB0_986

; __device__ __forceinline__ unsigned xb_ld(unsigned* p)              { return __hip_atomic_load(p, __ATOMIC_RELAXED, __HIP_MEMORY_SCOPE_AGENT); }
; __device__ __forceinline__ unsigned xb_add(unsigned* p, unsigned v) { return __hip_atomic_fetch_add(p, v, __ATOMIC_RELAXED, __HIP_MEMORY_SCOPE_AGENT); }
; __device__ __forceinline__ void xcd_barrier_complete(unsigned* bar, unsigned x, unsigned& nloc, unsigned& nx) {
;     const unsigned G = gridDim.x * gridDim.y * gridDim.z;
;     unsigned sum, cnt, mine, sp = 0u;
;     for (;;) {
;         sum = 0u; cnt = 0u; mine = 0u;
; #pragma unroll
;         for (unsigned j = 0; j < 16; ++j) { const unsigned c = xb_ld(&bar[XB_XCNT(j)]); sum += c; cnt += (c > 0u) ? 1u : 0u; mine = (j == x) ? c : mine; }
; __device__ __forceinline__ void xcd_barrier(const XcdBarrier& b) {
;     asm volatile("s_waitcnt vmcnt(0)" ::: "memory");
;     __syncthreads();
;     if (threadIdx.x == 0) {
;         unsigned* bar = b.bar;
;         __builtin_amdgcn_s_waitcnt(0);
;         unsigned nloc = b.st[0], nx = b.st[1];
;         if (nloc == 0u) { xcd_barrier_complete(bar, b.x, nloc, nx); b.st[0] = nloc; b.st[1] = nx; }
;         const unsigned old = xb_add(&bar[XB_XSUB(b.x)], 1u);
;         const unsigned gen = old / nloc;
.LBB0_1120:
	s_load_dwordx2 s[4:5], s[58:59], 0xb8
	s_waitcnt lgkmcnt(0)
	s_getreg_b32 s2, hwreg(HW_REG_XCC_ID, 0, 4)
	s_waitcnt vmcnt(0)
	s_barrier
	v_readfirstlane_b32 s100, v228
	s_cmp_eq_u32 s100, 64
	s_cbranch_scc0 .Lskip_wb0
	buffer_wbl2 sc1
	s_waitcnt vmcnt(0)
.Lskip_wb0:
	s_and_saveexec_b64 s[0:1], s[62:63]
	s_xor_b64 s[0:1], exec, s[0:1]
	s_mov_b32 s53, 0x10000
	s_mov_b32 s60, 0x18000
	s_mov_b32 s80, 0x8000
	s_mov_b32 s81, 0x40000
	s_cbranch_execz .LBB0_1173
	v_readlane_b32 s6, v254, 31
	s_waitcnt vmcnt(0) expcnt(0) lgkmcnt(0)
	s_and_b32 s2, s2, 15
	v_mov_b32_e32 v0, s6
	ds_read_b32 v2, v0
	v_readlane_b32 s6, v254, 32
	s_waitcnt lgkmcnt(0)
	v_cmp_ne_u32_e32 vcc, 0, v2
	v_mov_b32_e32 v0, s6
	ds_read_b32 v0, v0
	s_cbranch_vccnz .LBB0_1136
	s_add_u32 s6, s4, 0x9780200
	s_addc_u32 s7, s5, 0
	s_add_u32 s8, s4, 0x9780400
	s_addc_u32 s9, s5, 0
	s_add_u32 s10, s4, 0x9780500
	s_addc_u32 s11, s5, 0
	s_add_u32 s12, s4, 0x9780600
	s_addc_u32 s13, s5, 0
	s_add_u32 s14, s4, 0x9780700
	s_addc_u32 s15, s5, 0
	s_add_u32 s18, s4, 0x9780800
	s_addc_u32 s19, s5, 0
	s_add_u32 s20, s4, 0x9780900
	s_addc_u32 s21, s5, 0
	s_add_u32 s22, s4, 0x9780a00
	s_addc_u32 s23, s5, 0
	s_add_u32 s24, s4, 0x9780b00
	s_addc_u32 s25, s5, 0
	s_add_u32 s26, s4, 0x9780c00
	s_addc_u32 s27, s5, 0
	s_add_u32 s28, s4, 0x9780d00
	s_addc_u32 s29, s5, 0
	s_add_u32 s30, s4, 0x9780e00
	s_addc_u32 s31, s5, 0
	s_add_u32 s34, s4, 0x9780f00
	s_addc_u32 s35, s5, 0
	s_add_u32 s36, s4, 0x9781000
	s_addc_u32 s37, s5, 0
	s_add_u32 s38, s4, 0x9781100
	s_addc_u32 s39, s5, 0
	s_add_u32 s40, s4, 0x9781200
	s_addc_u32 s41, s5, 0
	s_add_u32 s42, s4, 0x9781300
	s_addc_u32 s43, s5, 0
	s_mov_b32 s50, 1
	s_branch .LBB0_1124
